# grid barrier (6 in-loop sites): waiting workgroups poll the top-level generation word directly instead of the per-XCD word, removing one atomic hop per barrier
# speedup vs baseline: 1.0392x; 1.0006x over previous
.LBB0_421:
	s_or_b64 exec, exec, s[10:11]
	v_cvt_f32_u32_e32 v5, v3
	s_waitcnt vmcnt(0)
	v_readfirstlane_b32 s8, v4
	v_sub_u32_e32 v4, 0, v3
	v_rcp_iflag_f32_e32 v5, v5
	v_add_u32_e32 v6, s8, v0
	v_mul_f32_e32 v5, 0x4f7ffffe, v5
	v_cvt_u32_f32_e32 v5, v5
	v_mul_lo_u32 v0, v4, v5
	v_mul_hi_u32 v0, v5, v0
	v_add_u32_e32 v0, v5, v0
	v_mul_hi_u32 v0, v6, v0
	v_mul_lo_u32 v4, v0, v3
	v_sub_u32_e32 v4, v6, v4
	v_add_u32_e32 v5, 1, v0
	v_cmp_ge_u32_e32 vcc, v4, v3
	s_nop 1
	v_cndmask_b32_e32 v0, v0, v5, vcc
	v_sub_u32_e32 v5, v4, v3
	v_cndmask_b32_e32 v4, v4, v5, vcc
	v_add_u32_e32 v5, 1, v0
	v_cmp_ge_u32_e32 vcc, v4, v3
	v_add_u32_e32 v4, 1, v6
	s_nop 0
	v_cndmask_b32_e32 v0, v0, v5, vcc
	v_mul_lo_u32 v5, v3, v0
	v_add_u32_e32 v3, v5, v3
	v_cmp_ne_u32_e32 vcc, v4, v3
	s_and_saveexec_b64 s[8:9], vcc
	s_xor_b64 s[8:9], exec, s[8:9]
	s_cbranch_execz .LBB0_435
	s_waitcnt lgkmcnt(0)
	v_readlane_b32 s12, v254, 17
	v_readlane_b32 s13, v254, 18
	s_nop 4
	global_load_dword v2, v1, s[12:13] sc1
	s_nop 0
	s_nop 0
	s_waitcnt vmcnt(0)
	v_cmp_eq_u32_e32 vcc, v2, v0
	s_and_saveexec_b64 s[10:11], vcc
	s_cbranch_execz .LBB0_434
	s_mov_b32 s22, 1
	s_mov_b64 s[14:15], 0
	s_branch .LBB0_425

.LBB0_452:
	s_or_b64 exec, exec, s[8:9]
	s_mov_b64 s[8:9], exec
	v_mbcnt_lo_u32_b32 v0, s8, 0
	v_mbcnt_hi_u32_b32 v0, s9, v0
	v_cmp_eq_u32_e32 vcc, 0, v0
	s_waitcnt vmcnt(0)
	buffer_inv sc1
	s_and_saveexec_b64 s[10:11], vcc
	s_cbranch_execz .LBB0_454
	s_bcnt1_i32_b64 s8, s[8:9]
	v_mov_b32_e32 v0, s8
	v_mov_b32_e32 v2, 0x2000
	s_nop 0

.LBB0_1222:
	s_or_b64 exec, exec, s[8:9]
	s_mov_b64 s[8:9], exec
	v_mbcnt_lo_u32_b32 v0, s8, 0
	v_mbcnt_hi_u32_b32 v0, s9, v0
	v_cmp_eq_u32_e32 vcc, 0, v0
	s_waitcnt vmcnt(0)
	buffer_inv sc1
	s_and_saveexec_b64 s[10:11], vcc
	s_cbranch_execz .LBB0_356
	s_bcnt1_i32_b64 s8, s[8:9]
	v_mov_b32_e32 v0, s8
	v_mov_b32_e32 v2, 0x2000
	s_nop 0
	s_branch .LBB0_356
